# hand-written W_o epilogue with 5-row load prefetch; attention mask via bfe+and
# speedup vs baseline: 1.0386x; 1.0076x over previous
.LBB0_717:
	s_add_i32 s0, s41, 2
	s_min_u32 s72, s0, s36
	s_cmp_gt_i32 s40, 0
	s_cselect_b32 s0, -1, 2
	s_add_i32 s101, s0, s40
	s_lshl_b64 s[98:99], s[72:73], 7
	s_add_u32 s98, s6, s98
	s_addc_u32 s99, s7, s99
	s_lshl_b32 s43, s72, 6
	s_add_i32 s43, s43, s25
	s_lshl_b32 s101, s101, 15
	s_add_i32 s100, s101, s16
	s_add_i32 s101, s101, s20
	s_cmp_gt_i32 s41, s35
	s_cbranch_scc1 .Lattn_idle
	s_lshl_b32 s0, s40, 15
	s_add_i32 s42, s0, 0
	v_add_u32_e32 v0, s42, v151
	v_add_u32_e32 v8, v0, v159
	v_add_u32_e32 v9, v0, v160
	v_add_u32_e32 v10, v0, v161
	v_add_u32_e32 v11, v0, v162
	v_add_u32_e32 v12, v0, v163
	v_add_u32_e32 v13, v0, v164
	v_add_u32_e32 v14, v0, v165
	v_add_u32_e32 v0, v0, v166
	ds_read_b128 v[240:243], v8
	ds_read_b128 v[244:247], v9
	ds_read_b128 v[248:251], v10
	ds_read_b128 v[252:255], v11
	ds_read_b128 v[208:211], v12
	ds_read_b128 v[222:225], v13
	ds_read_b128 v[226:229], v14
	ds_read_b128 v[230:233], v0
	s_waitcnt lgkmcnt(7)
	v_mfma_f32_32x32x16_bf16 v[96:111], v[240:243], v[112:115], 0
	v_mov_b32_e32 v191, 0
	v_mov_b32_e32 v184, v152
	v_ashrrev_i32_e32 v185, 4, v184
	v_add_u32_e32 v190, s14, v185
	v_xor_b32_e32 v187, v190, v184
	ds_read_b128 v[240:243], v8 offset:8192
	s_waitcnt lgkmcnt(7)
	v_mfma_f32_32x32x16_bf16 v[96:111], v[244:247], v[116:119], v[96:111]
	v_add_u32_e32 v188, s43, v190
	v_lshlrev_b32_e32 v189, 3, v187
	v_lshrrev_b32_e32 v182, 8, v188
	v_mov_b32_e32 v192, s29
	v_lshrrev_b32_e32 v188, 3, v188
	ds_read_b128 v[244:247], v9 offset:8192
	s_waitcnt lgkmcnt(7)
	v_mfma_f32_32x32x16_bf16 v[96:111], v[248:251], v[120:123], v[96:111]
	v_lshlrev_b32_e32 v187, 7, v187
	v_mad_i32_i24 v182, v182, s33, v192
	v_and_or_b32 v188, v188, 30, s27
	v_and_b32_e32 v187, 0x600, v187
	v_lshlrev_b32_e32 v190, 5, v190
	ds_read_b128 v[248:251], v10 offset:8192
	s_waitcnt lgkmcnt(7)
	v_mfma_f32_32x32x16_bf16 v[96:111], v[252:255], v[124:127], v[96:111]
	v_ashrrev_i32_e32 v183, 31, v182
	v_lshl_or_b32 v187, v188, 11, v187
	v_and_b32_e32 v190, 0x1e0, v190
	v_and_b32_e32 v188, 24, v189
	v_or3_b32 v190, v187, v190, v188
	ds_read_b128 v[252:255], v11 offset:8192
	s_waitcnt lgkmcnt(7)
	v_mfma_f32_32x32x16_bf16 v[96:111], v[208:211], v[128:131], v[96:111]
	v_lshlrev_b64 v[182:183], 17, v[182:183]
	v_ashrrev_i32_e32 v186, 3, v184
	v_lshl_add_u64 v[182:183], s[70:71], 0, v[182:183]
	v_lshlrev_b32_e32 v190, 1, v190
	v_lshl_add_u64 v[182:183], v[182:183], 0, v[190:191]
	ds_read_b128 v[208:211], v12 offset:8192
	s_waitcnt lgkmcnt(7)
	v_mfma_f32_32x32x16_bf16 v[96:111], v[222:225], v[132:135], v[96:111]
	v_add_u32_e32 v190, s15, v186
	v_lshrrev_b32_e32 v187, 1, v190
	v_xor_b32_e32 v187, v187, v184
	v_lshlrev_b32_e32 v190, 13, v190
	v_lshlrev_b32_e32 v187, 4, v187
	ds_read_b128 v[222:225], v13 offset:8192
	s_waitcnt lgkmcnt(7)
	v_mfma_f32_32x32x16_bf16 v[96:111], v[226:229], v[136:139], v[96:111]
	v_and_or_b32 v190, v187, s28, v190
	s_mov_b32 m0, s100
	s_nop 0
	global_load_lds_dwordx4 v[182:183], off
	s_add_i32 m0, s100, 0x4000
	ds_read_b128 v[226:229], v14 offset:8192
	s_waitcnt lgkmcnt(7)
	v_mfma_f32_32x32x16_bf16 v[96:111], v[230:233], v[140:143], v[96:111]
	s_nop 0
	global_load_lds_dwordx4 v190, s[98:99]
	v_add_u32_e32 v190, s17, v185
	v_xor_b32_e32 v185, v190, v184
	v_add_u32_e32 v187, s43, v190
	ds_read_b128 v[230:233], v0 offset:8192
	s_waitcnt lgkmcnt(7)
	v_mfma_f32_32x32x16_bf16 v[80:95], v[240:243], v[112:115], 0
	v_lshlrev_b32_e32 v188, 3, v185
	v_lshrrev_b32_e32 v182, 8, v187
	v_lshrrev_b32_e32 v187, 3, v187
	v_lshlrev_b32_e32 v185, 7, v185
	v_mad_i32_i24 v182, v182, s33, v192
	s_waitcnt lgkmcnt(6)
	v_mfma_f32_32x32x16_bf16 v[80:95], v[244:247], v[116:119], v[80:95]
	v_and_or_b32 v187, v187, 30, s27
	v_and_b32_e32 v185, 0x600, v185
	v_lshlrev_b32_e32 v190, 5, v190
	v_ashrrev_i32_e32 v183, 31, v182
	v_lshl_or_b32 v185, v187, 11, v185
	s_waitcnt lgkmcnt(5)
	v_mfma_f32_32x32x16_bf16 v[80:95], v[248:251], v[120:123], v[80:95]
	v_and_b32_e32 v190, 0x1e0, v190
	v_and_b32_e32 v187, 24, v188
	v_or3_b32 v190, v185, v190, v187
	v_lshlrev_b64 v[182:183], 17, v[182:183]
	v_lshl_add_u64 v[182:183], s[70:71], 0, v[182:183]
	s_waitcnt lgkmcnt(4)
	v_mfma_f32_32x32x16_bf16 v[80:95], v[252:255], v[124:127], v[80:95]
	v_lshlrev_b32_e32 v190, 1, v190
	v_lshl_add_u64 v[182:183], v[182:183], 0, v[190:191]
	v_add_u32_e32 v190, s19, v186
	v_lshrrev_b32_e32 v185, 1, v190
	v_xor_b32_e32 v184, v185, v184
	s_waitcnt lgkmcnt(3)
	v_mfma_f32_32x32x16_bf16 v[80:95], v[208:211], v[128:131], v[80:95]
	v_lshlrev_b32_e32 v190, 13, v190
	v_lshlrev_b32_e32 v184, 4, v184
	v_and_or_b32 v190, v184, s28, v190
	s_mov_b32 m0, s101
	s_nop 0
	s_waitcnt lgkmcnt(2)
	v_mfma_f32_32x32x16_bf16 v[80:95], v[222:225], v[132:135], v[80:95]
	global_load_lds_dwordx4 v[182:183], off
	s_add_i32 m0, s101, 0x4000
	s_nop 0
	global_load_lds_dwordx4 v190, s[98:99]
	s_waitcnt lgkmcnt(1)
	v_mfma_f32_32x32x16_bf16 v[80:95], v[226:229], v[136:139], v[80:95]
	s_waitcnt lgkmcnt(0)
	v_mfma_f32_32x32x16_bf16 v[80:95], v[230:233], v[140:143], v[80:95]
	v_add_u32_e32 v207, s42, v155
	v_add_u32_e32 v221, v207, v168
	v_add_u32_e32 v207, v207, v167
	ds_read_b128 v[240:243], v207 offset:16384
	ds_read_b128 v[244:247], v207 offset:20480
	ds_read_b128 v[248:251], v207 offset:24576
	ds_read_b128 v[252:255], v207 offset:28672
	ds_read_b128 v[208:211], v221 offset:16384
	ds_read_b128 v[222:225], v221 offset:20480
	ds_read_b128 v[226:229], v221 offset:24576
	ds_read_b128 v[230:233], v221 offset:28672
	s_cmpk_gt_i32 s37, 0x7f
	s_cbranch_scc1 .LBB0_720
	v_add_u32_e32 v0, s37, v174
	v_add_u32_e32 v186, 62, v0
	v_med3_i32 v5, v186, 0, v214
	v_max_i32_e32 v186, 32, v186
	v_subrev_u32_e32 v186, 32, v186
	v_add_u32_e32 v187, 61, v0
	v_min_u32_e32 v186, 0x80, v186
	v_lshl_add_u32 v193, v186, 2, s2
	v_max_i32_e32 v186, 32, v187
	v_subrev_u32_e32 v186, 32, v186
	v_add_u32_e32 v188, 60, v0
	v_min_u32_e32 v186, 0x80, v186
	v_lshl_add_u32 v201, v186, 2, s2
	v_max_i32_e32 v186, 32, v188
	v_subrev_u32_e32 v186, 32, v186
	v_add_u32_e32 v189, 59, v0
	v_min_u32_e32 v186, 0x80, v186
	v_lshl_add_u32 v202, v186, 2, s2
	v_max_i32_e32 v186, 32, v189
	v_subrev_u32_e32 v186, 32, v186
	v_add_u32_e32 v190, 58, v0
	v_min_u32_e32 v186, 0x80, v186
	v_lshl_add_u32 v203, v186, 2, s2
	v_max_i32_e32 v186, 32, v190
	v_subrev_u32_e32 v186, 32, v186
	v_add_u32_e32 v191, 57, v0
	v_min_u32_e32 v186, 0x80, v186
	v_lshl_add_u32 v204, v186, 2, s2
	v_max_i32_e32 v186, 32, v191
	v_add_u32_e32 v181, 63, v0
	v_subrev_u32_e32 v186, 32, v186
	v_med3_i32 v4, v181, 0, v214
	v_add_u32_e32 v192, 56, v0
	v_max_i32_e32 v181, 32, v181
	v_min_u32_e32 v186, 0x80, v186
	v_add_u32_e32 v194, 47, v0
	v_add_u32_e32 v195, 46, v0
	v_add_u32_e32 v196, 45, v0
	v_add_u32_e32 v197, 44, v0
	v_add_u32_e32 v198, 43, v0
	v_add_u32_e32 v199, 42, v0
	v_add_u32_e32 v200, 41, v0
	v_add_u32_e32 v0, 40, v0
	v_subrev_u32_e32 v181, 32, v181
	v_lshl_add_u32 v205, v186, 2, s2
	v_max_i32_e32 v186, 32, v192
	v_med3_i32 v6, v187, 0, v214
	v_med3_i32 v7, v188, 0, v214
	v_med3_i32 v8, v189, 0, v214
	v_med3_i32 v9, v190, 0, v214
	v_med3_i32 v10, v191, 0, v214
	v_med3_i32 v11, v192, 0, v214
	v_med3_i32 v12, v194, 0, v214
	v_med3_i32 v13, v195, 0, v214
	v_med3_i32 v14, v196, 0, v214
	v_med3_i32 v15, v197, 0, v214
	v_med3_i32 v182, v198, 0, v214
	v_med3_i32 v183, v199, 0, v214
	v_med3_i32 v184, v200, 0, v214
	v_med3_i32 v185, v0, 0, v214
	v_min_u32_e32 v181, 0x80, v181
	v_subrev_u32_e32 v186, 32, v186
	v_lshl_add_u32 v4, v4, 2, s2
	v_lshl_add_u32 v5, v5, 2, s2
	v_lshl_add_u32 v6, v6, 2, s2
	v_lshl_add_u32 v7, v7, 2, s2
	v_lshl_add_u32 v8, v8, 2, s2
	v_lshl_add_u32 v9, v9, 2, s2
	v_lshl_add_u32 v10, v10, 2, s2
	v_lshl_add_u32 v11, v11, 2, s2
	v_lshl_add_u32 v12, v12, 2, s2
	v_lshl_add_u32 v13, v13, 2, s2
	v_lshl_add_u32 v14, v14, 2, s2
	v_lshl_add_u32 v15, v15, 2, s2
	v_lshl_add_u32 v182, v182, 2, s2
	v_lshl_add_u32 v183, v183, 2, s2
	v_lshl_add_u32 v184, v184, 2, s2
	v_lshl_add_u32 v185, v185, 2, s2
	v_lshl_add_u32 v181, v181, 2, s2
	v_min_u32_e32 v186, 0x80, v186
	ds_read_b32 v4, v4
	ds_read_b32 v5, v5
	ds_read_b32 v6, v6
	ds_read_b32 v7, v7
	ds_read_b32 v8, v8
	ds_read_b32 v9, v9
	ds_read_b32 v10, v10
	ds_read_b32 v11, v11
	ds_read_b32 v12, v12
	ds_read_b32 v13, v13
	ds_read_b32 v14, v14
	ds_read_b32 v15, v15
	ds_read_b32 v182, v182
	ds_read_b32 v183, v183
	ds_read_b32 v184, v184
	ds_read_b32 v185, v185
	v_lshl_add_u32 v206, v186, 2, s2
	ds_read_b32 v186, v181
	ds_read_b32 v187, v193
	ds_read_b32 v188, v201
	ds_read_b32 v189, v202
	ds_read_b32 v190, v203
	ds_read_b32 v191, v204
	ds_read_b32 v192, v205
	ds_read_b32 v193, v206
	v_max_i32_e32 v181, 32, v194
	v_max_i32_e32 v194, 32, v195
	v_subrev_u32_e32 v194, 32, v194
	v_min_u32_e32 v194, 0x80, v194
	v_lshl_add_u32 v195, v194, 2, s2
	v_max_i32_e32 v194, 32, v196
	v_subrev_u32_e32 v194, 32, v194
	v_min_u32_e32 v194, 0x80, v194
	v_lshl_add_u32 v196, v194, 2, s2
	v_max_i32_e32 v194, 32, v197
	v_subrev_u32_e32 v194, 32, v194
	v_min_u32_e32 v194, 0x80, v194
	v_lshl_add_u32 v197, v194, 2, s2
	v_max_i32_e32 v194, 32, v198
	v_subrev_u32_e32 v194, 32, v194
	v_min_u32_e32 v194, 0x80, v194
	v_lshl_add_u32 v198, v194, 2, s2
	v_max_i32_e32 v194, 32, v199
	v_subrev_u32_e32 v194, 32, v194
	v_min_u32_e32 v194, 0x80, v194
	v_lshl_add_u32 v199, v194, 2, s2
	v_max_i32_e32 v194, 32, v200
	v_subrev_u32_e32 v181, 32, v181
	v_subrev_u32_e32 v194, 32, v194
	v_max_i32_e32 v0, 32, v0
	v_min_u32_e32 v181, 0x80, v181
	v_min_u32_e32 v194, 0x80, v194
	v_subrev_u32_e32 v0, 32, v0
	v_lshl_add_u32 v181, v181, 2, s2
	v_lshl_add_u32 v200, v194, 2, s2
	v_min_u32_e32 v0, 0x80, v0
	v_lshl_add_u32 v0, v0, 2, s2
	ds_read_b32 v194, v181
	ds_read_b32 v195, v195
	ds_read_b32 v196, v196
	ds_read_b32 v197, v197
	ds_read_b32 v198, v198
	ds_read_b32 v199, v199
	ds_read_b32 v200, v200
	ds_read_b32 v201, v0
	s_waitcnt lgkmcnt(0)
	v_pk_add_f32 v[110:111], v[110:111], v[184:185]
	v_pk_add_f32 v[108:109], v[108:109], v[182:183]
	v_pk_add_f32 v[106:107], v[106:107], v[14:15]
	v_pk_add_f32 v[104:105], v[104:105], v[12:13]
	v_pk_add_f32 v[102:103], v[102:103], v[10:11]
	v_pk_add_f32 v[100:101], v[100:101], v[8:9]
	v_pk_add_f32 v[98:99], v[98:99], v[6:7]
	v_pk_add_f32 v[96:97], v[96:97], v[4:5]
	v_pk_add_f32 v[94:95], v[94:95], v[200:201]
	v_pk_add_f32 v[92:93], v[92:93], v[198:199]
	v_pk_add_f32 v[90:91], v[90:91], v[196:197]
	v_pk_add_f32 v[88:89], v[88:89], v[194:195]
	v_pk_add_f32 v[86:87], v[86:87], v[192:193]
	v_pk_add_f32 v[84:85], v[84:85], v[190:191]
	v_pk_add_f32 v[82:83], v[82:83], v[188:189]
	v_pk_add_f32 v[80:81], v[80:81], v[186:187]

.LBB0_722:
	v_cndmask_b32_e64 v145, v4, v145, s[0:1]
	v_lshrrev_b32_e32 v4, v154, v148
	v_sub_f32_e32 v5, v96, v145
	v_bfe_i32 v6, v4, 0, 1
	v_exp_f32_e32 v5, v5
	s_nop 0
	v_and_b32_e32 v148, v6, v5
	v_sub_f32_e32 v6, v97, v145
	v_exp_f32_e32 v6, v6
	v_bfe_i32 v7, v4, 1, 1
	v_and_b32_e32 v181, v7, v6
	v_bfe_i32 v7, v4, 2, 1
	v_add_f32_e32 v5, 0, v148
	v_sub_f32_e32 v6, v98, v145
	v_exp_f32_e32 v6, v6
	v_add_f32_e32 v5, v181, v5
	v_and_b32_e32 v182, v7, v6
	v_bfe_i32 v7, v4, 3, 1
	v_sub_f32_e32 v6, v99, v145
	v_exp_f32_e32 v6, v6
	v_add_f32_e32 v5, v182, v5
	v_and_b32_e32 v183, v7, v6
	v_bfe_i32 v7, v4, 4, 1
	v_sub_f32_e32 v6, v100, v145
	v_exp_f32_e32 v6, v6
	v_add_f32_e32 v5, v183, v5
	v_and_b32_e32 v184, v7, v6
	v_bfe_i32 v7, v4, 5, 1
	v_sub_f32_e32 v6, v101, v145
	v_exp_f32_e32 v6, v6
	v_add_f32_e32 v5, v184, v5
	v_and_b32_e32 v185, v7, v6
	v_bfe_i32 v7, v4, 6, 1
	v_sub_f32_e32 v6, v102, v145
	v_exp_f32_e32 v6, v6
	v_add_f32_e32 v5, v185, v5
	v_and_b32_e32 v186, v7, v6
	v_bfe_i32 v7, v4, 7, 1
	v_sub_f32_e32 v6, v103, v145
	v_exp_f32_e32 v6, v6
	v_add_f32_e32 v5, v186, v5
	v_and_b32_e32 v187, v7, v6
	v_bfe_i32 v7, v4, 16, 1
	v_sub_f32_e32 v6, v104, v145
	v_exp_f32_e32 v6, v6
	v_add_f32_e32 v5, v187, v5
	v_and_b32_e32 v96, v7, v6
	v_bfe_i32 v7, v4, 17, 1
	v_sub_f32_e32 v6, v105, v145
	v_exp_f32_e32 v6, v6
	v_add_f32_e32 v5, v96, v5
	v_and_b32_e32 v97, v7, v6
	v_bfe_i32 v7, v4, 18, 1
	v_sub_f32_e32 v6, v106, v145
	v_exp_f32_e32 v6, v6
	v_add_f32_e32 v5, v97, v5
	v_and_b32_e32 v98, v7, v6
	v_bfe_i32 v7, v4, 19, 1
	v_sub_f32_e32 v6, v107, v145
	v_exp_f32_e32 v6, v6
	v_add_f32_e32 v5, v98, v5
	v_and_b32_e32 v99, v7, v6
	v_bfe_i32 v7, v4, 20, 1
	v_sub_f32_e32 v6, v108, v145
	v_exp_f32_e32 v6, v6
	v_add_f32_e32 v5, v99, v5
	v_and_b32_e32 v100, v7, v6
	v_bfe_i32 v7, v4, 21, 1
	v_sub_f32_e32 v6, v109, v145
	v_exp_f32_e32 v6, v6
	v_add_f32_e32 v5, v100, v5
	v_and_b32_e32 v101, v7, v6
	v_bfe_i32 v7, v4, 22, 1
	v_sub_f32_e32 v6, v110, v145
	v_exp_f32_e32 v6, v6
	v_bfe_i32 v4, v4, 23, 1
	v_and_b32_e32 v102, v7, v6
	v_add_f32_e32 v5, v101, v5
	v_sub_f32_e32 v6, v111, v145
	v_exp_f32_e32 v6, v6
	v_add_f32_e32 v5, v102, v5
	v_and_b32_e32 v103, v4, v6
	v_lshrrev_b32_e32 v12, v154, v149
	v_add_f32_e32 v4, v103, v5
	v_sub_f32_e32 v5, v80, v145
	v_exp_f32_e32 v5, v5
	v_bfe_i32 v6, v12, 0, 1
	v_and_b32_e32 v13, v6, v5
	v_bfe_i32 v6, v12, 1, 1
	v_bfe_i32 v7, v12, 17, 1
	v_sub_f32_e32 v5, v81, v145
	v_exp_f32_e32 v5, v5
	v_bfe_i32 v8, v12, 18, 1
	v_and_b32_e32 v14, v6, v5
	v_bfe_i32 v6, v12, 2, 1
	v_sub_f32_e32 v5, v82, v145
	v_exp_f32_e32 v5, v5
	v_add_f32_e32 v4, v13, v4
	v_and_b32_e32 v15, v6, v5
	v_bfe_i32 v6, v12, 3, 1
	v_sub_f32_e32 v5, v83, v145
	v_exp_f32_e32 v5, v5
	v_add_f32_e32 v4, v14, v4
	v_and_b32_e32 v80, v6, v5
	v_bfe_i32 v6, v12, 4, 1
	v_sub_f32_e32 v5, v84, v145
	v_exp_f32_e32 v5, v5
	v_add_f32_e32 v4, v15, v4
	v_and_b32_e32 v81, v6, v5
	v_bfe_i32 v6, v12, 5, 1
	v_sub_f32_e32 v5, v85, v145
	v_exp_f32_e32 v5, v5
	v_bfe_i32 v9, v12, 19, 1
	v_and_b32_e32 v82, v6, v5
	v_bfe_i32 v6, v12, 6, 1
	v_sub_f32_e32 v5, v86, v145
	v_exp_f32_e32 v5, v5
	v_add_f32_e32 v4, v80, v4
	v_and_b32_e32 v83, v6, v5
	v_bfe_i32 v6, v12, 7, 1
	v_sub_f32_e32 v5, v87, v145
	v_exp_f32_e32 v5, v5
	v_bfe_i32 v10, v12, 20, 1
	v_and_b32_e32 v84, v6, v5
	v_bfe_i32 v6, v12, 16, 1
	v_sub_f32_e32 v5, v88, v145
	v_exp_f32_e32 v5, v5
	s_nop 0
	v_and_b32_e32 v5, v6, v5
	v_sub_f32_e32 v6, v89, v145
	v_exp_f32_e32 v6, v6
	s_nop 0
	v_and_b32_e32 v6, v7, v6
	v_sub_f32_e32 v7, v90, v145
	v_exp_f32_e32 v7, v7
	s_nop 0
	v_and_b32_e32 v7, v8, v7
	v_sub_f32_e32 v8, v91, v145
	v_exp_f32_e32 v8, v8
	v_add_f32_e32 v4, v81, v4
	v_and_b32_e32 v8, v9, v8
	v_sub_f32_e32 v9, v92, v145
	v_exp_f32_e32 v9, v9
	v_add_f32_e32 v4, v82, v4
	v_and_b32_e32 v9, v10, v9
	v_sub_f32_e32 v10, v93, v145
	v_exp_f32_e32 v10, v10
	v_add_f32_e32 v4, v83, v4
	v_add_f32_e32 v4, v84, v4
	v_bfe_i32 v11, v12, 21, 1
	v_add_f32_e32 v4, v5, v4
	v_and_b32_e32 v10, v11, v10
	v_sub_f32_e32 v11, v94, v145
	v_bfe_i32 v85, v12, 22, 1
	v_add_f32_e32 v4, v6, v4
	v_exp_f32_e32 v11, v11
	v_add_f32_e32 v4, v7, v4
	v_and_b32_e32 v11, v85, v11
	v_sub_f32_e32 v85, v95, v145
	v_exp_f32_e32 v85, v85
	v_add_f32_e32 v4, v8, v4
	v_add_f32_e32 v4, v9, v4
	v_bfe_i32 v12, v12, 23, 1
	v_add_f32_e32 v4, v10, v4
	v_and_b32_e32 v12, v12, v85
	v_add_f32_e32 v4, v11, v4
	v_cndmask_b32_e64 v0, v0, 1.0, s[0:1]
	v_add_f32_e32 v4, v12, v4
	v_fmac_f32_e32 v4, v180, v0
	v_add_u32_e32 v0, s42, v155
	v_add_u32_e32 v85, v0, v169
	v_add_u32_e32 v0, v0, v170
	v_cvt_pk_bf16_f32 v86, v148, v181
	v_cvt_pk_bf16_f32 v87, v182, v183
	v_cvt_pk_bf16_f32 v88, v184, v185
	v_cvt_pk_bf16_f32 v89, v186, v187
	v_cvt_pk_bf16_f32 v7, v7, v8
	v_cvt_pk_bf16_f32 v8, v9, v10
	v_cvt_pk_bf16_f32 v9, v11, v12
	v_cvt_pk_bf16_f32 v6, v5, v6
	v_mov_b32_e32 v180, v4
	s_waitcnt lgkmcnt(0)
	v_mfma_f32_32x32x16_bf16 v[64:79], v[240:243], v[86:89], v[64:79]
	ds_read_b128 v[240:243], v85 offset:16384
	v_mfma_f32_32x32x16_bf16 v[48:63], v[244:247], v[86:89], v[48:63]
	ds_read_b128 v[244:247], v85 offset:20480
	v_mfma_f32_32x32x16_bf16 v[32:47], v[248:251], v[86:89], v[32:47]
	ds_read_b128 v[248:251], v85 offset:24576
	v_mfma_f32_32x32x16_bf16 v[16:31], v[252:255], v[86:89], v[16:31]
	ds_read_b128 v[252:255], v85 offset:28672
	v_cvt_pk_bf16_f32 v86, v96, v97
	v_cvt_pk_bf16_f32 v87, v98, v99
	v_cvt_pk_bf16_f32 v88, v100, v101
	v_cvt_pk_bf16_f32 v89, v102, v103
	s_nop 1
	v_mfma_f32_32x32x16_bf16 v[64:79], v[208:211], v[86:89], v[64:79]
	ds_read_b128 v[208:211], v0 offset:16384
	v_mfma_f32_32x32x16_bf16 v[48:63], v[222:225], v[86:89], v[48:63]
	ds_read_b128 v[222:225], v0 offset:20480
	v_mfma_f32_32x32x16_bf16 v[32:47], v[226:229], v[86:89], v[32:47]
	ds_read_b128 v[226:229], v0 offset:24576
	v_mfma_f32_32x32x16_bf16 v[16:31], v[230:233], v[86:89], v[16:31]
	ds_read_b128 v[230:233], v0 offset:28672
	v_cvt_pk_bf16_f32 v86, v13, v14
	v_cvt_pk_bf16_f32 v87, v15, v80
	v_cvt_pk_bf16_f32 v88, v81, v82
	v_cvt_pk_bf16_f32 v89, v83, v84
	s_nop 1
	s_waitcnt lgkmcnt(7)
	v_mfma_f32_32x32x16_bf16 v[64:79], v[240:243], v[86:89], v[64:79]
	s_waitcnt lgkmcnt(6)
	v_mfma_f32_32x32x16_bf16 v[48:63], v[244:247], v[86:89], v[48:63]
	s_waitcnt lgkmcnt(5)
	v_mfma_f32_32x32x16_bf16 v[32:47], v[248:251], v[86:89], v[32:47]
	s_waitcnt lgkmcnt(4)
	v_mfma_f32_32x32x16_bf16 v[16:31], v[252:255], v[86:89], v[16:31]
	s_waitcnt lgkmcnt(3)
	v_mfma_f32_32x32x16_bf16 v[64:79], v[208:211], v[6:9], v[64:79]
	s_waitcnt lgkmcnt(2)
	v_mfma_f32_32x32x16_bf16 v[48:63], v[222:225], v[6:9], v[48:63]
	s_waitcnt lgkmcnt(1)
	v_mfma_f32_32x32x16_bf16 v[32:47], v[226:229], v[6:9], v[32:47]
	s_waitcnt lgkmcnt(0)
	v_mfma_f32_32x32x16_bf16 v[16:31], v[230:233], v[6:9], v[16:31]

.Lattn_idle:
	v_mov_b32_e32 v6, v152
	v_ashrrev_i32_e32 v7, 4, v6
	v_add_u32_e32 v0, s14, v7
	v_xor_b32_e32 v9, v0, v6
	v_add_u32_e32 v10, s43, v0
	v_lshlrev_b32_e32 v11, 3, v9
	v_lshrrev_b32_e32 v4, 8, v10
	v_mov_b32_e32 v12, s29
	v_lshrrev_b32_e32 v10, 3, v10
	v_lshlrev_b32_e32 v9, 7, v9
	v_mad_i32_i24 v4, v4, s33, v12
	v_and_or_b32 v10, v10, 30, s27
	v_and_b32_e32 v9, 0x600, v9
	v_lshlrev_b32_e32 v0, 5, v0
	v_ashrrev_i32_e32 v5, 31, v4
	v_lshl_or_b32 v9, v10, 11, v9
	v_and_b32_e32 v0, 0x1e0, v0
	v_and_b32_e32 v10, 24, v11
	v_or3_b32 v0, v9, v0, v10
	v_lshlrev_b64 v[4:5], 17, v[4:5]
	v_ashrrev_i32_e32 v8, 3, v6
	v_lshl_add_u64 v[4:5], s[70:71], 0, v[4:5]
	v_lshlrev_b32_e32 v0, 1, v0
	v_lshl_add_u64 v[4:5], v[4:5], 0, v[0:1]
	v_add_u32_e32 v0, s15, v8
	v_lshrrev_b32_e32 v9, 1, v0
	v_xor_b32_e32 v9, v9, v6
	v_lshlrev_b32_e32 v0, 13, v0
	v_lshlrev_b32_e32 v9, 4, v9
	v_and_or_b32 v0, v9, s28, v0
	s_mov_b32 m0, s100
	s_nop 0
	global_load_lds_dwordx4 v[4:5], off
	s_add_i32 m0, s100, 0x4000
	s_nop 0
	global_load_lds_dwordx4 v0, s[98:99]
	v_add_u32_e32 v0, s17, v7
	v_xor_b32_e32 v7, v0, v6
	v_add_u32_e32 v9, s43, v0
	v_lshlrev_b32_e32 v10, 3, v7
	v_lshrrev_b32_e32 v4, 8, v9
	v_lshrrev_b32_e32 v9, 3, v9
	v_lshlrev_b32_e32 v7, 7, v7
	v_mad_i32_i24 v4, v4, s33, v12
	v_and_or_b32 v9, v9, 30, s27
	v_and_b32_e32 v7, 0x600, v7
	v_lshlrev_b32_e32 v0, 5, v0
	v_ashrrev_i32_e32 v5, 31, v4
	v_lshl_or_b32 v7, v9, 11, v7
	v_and_b32_e32 v0, 0x1e0, v0
	v_and_b32_e32 v9, 24, v10
	v_or3_b32 v0, v7, v0, v9
	v_lshlrev_b64 v[4:5], 17, v[4:5]
	v_lshl_add_u64 v[4:5], s[70:71], 0, v[4:5]
	v_lshlrev_b32_e32 v0, 1, v0
	v_lshl_add_u64 v[4:5], v[4:5], 0, v[0:1]
	v_add_u32_e32 v0, s19, v8
	v_lshrrev_b32_e32 v7, 1, v0
	v_xor_b32_e32 v6, v7, v6
	v_lshlrev_b32_e32 v0, 13, v0
	v_lshlrev_b32_e32 v6, 4, v6
	v_and_or_b32 v0, v6, s28, v0
	s_mov_b32 m0, s101
	s_nop 0
	global_load_lds_dwordx4 v[4:5], off
	s_add_i32 m0, s101, 0x4000
	s_nop 0
	global_load_lds_dwordx4 v0, s[98:99]
	s_branch .LBB0_723

.LBB0_935:
	v_readlane_b32 s46, v237, 43
	v_readlane_b32 s47, v237, 44
	s_movk_i32 s48, 0x104
	s_lshl_b32 s13, s42, 8
	s_add_i32 s13, s13, s36
	s_lshl_b32 s0, s41, 8
	s_or_b32 s22, s0, s37
	s_ashr_i32 s15, s22, 5
	s_lshl_b32 s0, s13, 2
	s_add_i32 s0, s0, s15
	s_ashr_i32 s1, s0, 31
	s_lshl_b64 s[2:3], s[0:1], 11
	v_lshl_add_u64 v[182:183], v[166:167], 0, s[2:3]
	s_lshl_b64 s[2:3], s[0:1], 9
	v_or_b32_e32 v176, s2, v164
	v_mov_b32_e32 v177, s3
	v_or_b32_e32 v130, s13, v165
	v_or_b32_e32 v132, s22, v178
	v_ashrrev_i32_e32 v131, 31, v130
	v_ashrrev_i32_e32 v133, 31, v132
	v_lshlrev_b64 v[130:131], 11, v[130:131]
	v_lshl_add_u64 v[130:131], v[130:131], 0, v[132:133]
	v_cndmask_b32_e64 v176, v130, v176, s[6:7]
	v_cndmask_b32_e64 v177, v131, v177, s[6:7]
	v_lshl_add_u64 v[176:177], v[176:177], 2, s[8:9]
	s_movk_i32 s2, 0x2000
	s_and_b64 s[0:1], s[6:7], exec
	s_cselect_b32 s15, s2, 0x200
	s_mov_b32 s3, 0
	s_mov_b32 s2, 0x0
	v_lshl_add_u64 v[184:185], v[176:177], 0, s[2:3]
	global_load_dwordx4 v[130:133], v[184:185], off
	global_load_dwordx4 v[134:137], v[184:185], off offset:16
	s_mov_b32 s2, 0x20000
	v_lshl_add_u64 v[184:185], v[176:177], 0, s[2:3]
	global_load_dwordx4 v[138:141], v[184:185], off
	global_load_dwordx4 v[142:145], v[184:185], off offset:16
	s_mov_b32 s2, 0x40000
	v_lshl_add_u64 v[184:185], v[176:177], 0, s[2:3]
	global_load_dwordx4 v[146:149], v[184:185], off
	global_load_dwordx4 v[150:153], v[184:185], off offset:16
	s_mov_b32 s2, 0x60000
	v_lshl_add_u64 v[184:185], v[176:177], 0, s[2:3]
	global_load_dwordx4 v[154:157], v[184:185], off
	global_load_dwordx4 v[158:161], v[184:185], off offset:16
	s_mov_b32 s2, 0x100000
	v_lshl_add_u64 v[184:185], v[176:177], 0, s[2:3]
	global_load_dwordx4 v[168:171], v[184:185], off
	global_load_dwordx4 v[172:175], v[184:185], off offset:16
	s_waitcnt vmcnt(8)
	v_add_f32_e32 v126, v126, v130
	v_add_f32_e32 v127, v127, v131
	v_add_f32_e32 v128, v128, v132
	v_add_f32_e32 v129, v129, v133
	v_add_f32_e32 v122, v122, v134
	v_add_f32_e32 v123, v123, v135
	v_add_f32_e32 v124, v124, v136
	v_add_f32_e32 v125, v125, v137
	s_mov_b32 s2, 0x0
	v_lshl_add_u64 v[186:187], v[182:183], 0, s[2:3]
	global_store_dwordx4 v[186:187], v[126:129], off
	global_store_dwordx4 v[186:187], v[122:125], off offset:16
	s_mov_b32 s2, 0x120000
	v_lshl_add_u64 v[184:185], v[176:177], 0, s[2:3]
	global_load_dwordx4 v[130:133], v[184:185], off
	global_load_dwordx4 v[134:137], v[184:185], off offset:16
	s_waitcnt vmcnt(10)
	v_add_f32_e32 v118, v118, v138
	v_add_f32_e32 v119, v119, v139
	v_add_f32_e32 v120, v120, v140
	v_add_f32_e32 v121, v121, v141
	v_add_f32_e32 v114, v114, v142
	v_add_f32_e32 v115, v115, v143
	v_add_f32_e32 v116, v116, v144
	v_add_f32_e32 v117, v117, v145
	s_mov_b32 s2, 0x20000
	v_lshl_add_u64 v[186:187], v[182:183], 0, s[2:3]
	global_store_dwordx4 v[186:187], v[118:121], off
	global_store_dwordx4 v[186:187], v[114:117], off offset:16
	s_mov_b32 s2, 0x140000
	v_lshl_add_u64 v[184:185], v[176:177], 0, s[2:3]
	global_load_dwordx4 v[138:141], v[184:185], off
	global_load_dwordx4 v[142:145], v[184:185], off offset:16
	s_waitcnt vmcnt(12)
	v_add_f32_e32 v110, v110, v146
	v_add_f32_e32 v111, v111, v147
	v_add_f32_e32 v112, v112, v148
	v_add_f32_e32 v113, v113, v149
	v_add_f32_e32 v106, v106, v150
	v_add_f32_e32 v107, v107, v151
	v_add_f32_e32 v108, v108, v152
	v_add_f32_e32 v109, v109, v153
	s_mov_b32 s2, 0x40000
	v_lshl_add_u64 v[186:187], v[182:183], 0, s[2:3]
	global_store_dwordx4 v[186:187], v[110:113], off
	global_store_dwordx4 v[186:187], v[106:109], off offset:16
	s_mov_b32 s2, 0x160000
	v_lshl_add_u64 v[184:185], v[176:177], 0, s[2:3]
	global_load_dwordx4 v[146:149], v[184:185], off
	global_load_dwordx4 v[150:153], v[184:185], off offset:16
	s_waitcnt vmcnt(14)
	v_add_f32_e32 v102, v102, v154
	v_add_f32_e32 v103, v103, v155
	v_add_f32_e32 v104, v104, v156
	v_add_f32_e32 v105, v105, v157
	v_add_f32_e32 v98, v98, v158
	v_add_f32_e32 v99, v99, v159
	v_add_f32_e32 v100, v100, v160
	v_add_f32_e32 v101, v101, v161
	s_mov_b32 s2, 0x60000
	v_lshl_add_u64 v[186:187], v[182:183], 0, s[2:3]
	global_store_dwordx4 v[186:187], v[102:105], off
	global_store_dwordx4 v[186:187], v[98:101], off offset:16
	s_mov_b32 s2, s15
	v_lshl_add_u64 v[184:185], v[176:177], 0, s[2:3]
	global_load_dwordx4 v[154:157], v[184:185], off
	global_load_dwordx4 v[158:161], v[184:185], off offset:16
	s_waitcnt vmcnt(16)
	v_add_f32_e32 v94, v94, v168
	v_add_f32_e32 v95, v95, v169
	v_add_f32_e32 v96, v96, v170
	v_add_f32_e32 v97, v97, v171
	v_add_f32_e32 v90, v90, v172
	v_add_f32_e32 v91, v91, v173
	v_add_f32_e32 v92, v92, v174
	v_add_f32_e32 v93, v93, v175
	s_mov_b32 s2, 0x100000
	v_lshl_add_u64 v[186:187], v[182:183], 0, s[2:3]
	global_store_dwordx4 v[186:187], v[94:97], off
	global_store_dwordx4 v[186:187], v[90:93], off offset:16
	s_add_u32 s2, s15, 0x20000
	v_lshl_add_u64 v[184:185], v[176:177], 0, s[2:3]
	global_load_dwordx4 v[168:171], v[184:185], off
	global_load_dwordx4 v[172:175], v[184:185], off offset:16
	s_waitcnt vmcnt(16)
	v_add_f32_e32 v86, v86, v130
	v_add_f32_e32 v87, v87, v131
	v_add_f32_e32 v88, v88, v132
	v_add_f32_e32 v89, v89, v133
	v_add_f32_e32 v82, v82, v134
	v_add_f32_e32 v83, v83, v135
	v_add_f32_e32 v84, v84, v136
	v_add_f32_e32 v85, v85, v137
	s_mov_b32 s2, 0x120000
	v_lshl_add_u64 v[186:187], v[182:183], 0, s[2:3]
	global_store_dwordx4 v[186:187], v[86:89], off
	global_store_dwordx4 v[186:187], v[82:85], off offset:16
	s_add_u32 s2, s15, 0x40000
	v_lshl_add_u64 v[184:185], v[176:177], 0, s[2:3]
	global_load_dwordx4 v[130:133], v[184:185], off
	global_load_dwordx4 v[134:137], v[184:185], off offset:16
	s_waitcnt vmcnt(16)
	v_add_f32_e32 v78, v78, v138
	v_add_f32_e32 v79, v79, v139
	v_add_f32_e32 v80, v80, v140
	v_add_f32_e32 v81, v81, v141
	v_add_f32_e32 v74, v74, v142
	v_add_f32_e32 v75, v75, v143
	v_add_f32_e32 v76, v76, v144
	v_add_f32_e32 v77, v77, v145
	s_mov_b32 s2, 0x140000
	v_lshl_add_u64 v[186:187], v[182:183], 0, s[2:3]
	global_store_dwordx4 v[186:187], v[78:81], off
	global_store_dwordx4 v[186:187], v[74:77], off offset:16
	s_add_u32 s2, s15, 0x60000
	v_lshl_add_u64 v[184:185], v[176:177], 0, s[2:3]
	global_load_dwordx4 v[138:141], v[184:185], off
	global_load_dwordx4 v[142:145], v[184:185], off offset:16
	s_waitcnt vmcnt(16)
	v_add_f32_e32 v70, v70, v146
	v_add_f32_e32 v71, v71, v147
	v_add_f32_e32 v72, v72, v148
	v_add_f32_e32 v73, v73, v149
	v_add_f32_e32 v66, v66, v150
	v_add_f32_e32 v67, v67, v151
	v_add_f32_e32 v68, v68, v152
	v_add_f32_e32 v69, v69, v153
	s_mov_b32 s2, 0x160000
	v_lshl_add_u64 v[186:187], v[182:183], 0, s[2:3]
	global_store_dwordx4 v[186:187], v[70:73], off
	global_store_dwordx4 v[186:187], v[66:69], off offset:16
	s_add_u32 s2, s15, 0x100000
	v_lshl_add_u64 v[184:185], v[176:177], 0, s[2:3]
	global_load_dwordx4 v[146:149], v[184:185], off
	global_load_dwordx4 v[150:153], v[184:185], off offset:16
	s_waitcnt vmcnt(16)
	v_add_f32_e32 v62, v62, v154
	v_add_f32_e32 v63, v63, v155
	v_add_f32_e32 v64, v64, v156
	v_add_f32_e32 v65, v65, v157
	v_add_f32_e32 v58, v58, v158
	v_add_f32_e32 v59, v59, v159
	v_add_f32_e32 v60, v60, v160
	v_add_f32_e32 v61, v61, v161
	s_mov_b32 s2, 0x2000
	v_lshl_add_u64 v[186:187], v[182:183], 0, s[2:3]
	global_store_dwordx4 v[186:187], v[62:65], off
	global_store_dwordx4 v[186:187], v[58:61], off offset:16
	s_add_u32 s2, s15, 0x120000
	v_lshl_add_u64 v[184:185], v[176:177], 0, s[2:3]
	global_load_dwordx4 v[154:157], v[184:185], off
	global_load_dwordx4 v[158:161], v[184:185], off offset:16
	s_waitcnt vmcnt(16)
	v_add_f32_e32 v54, v54, v168
	v_add_f32_e32 v55, v55, v169
	v_add_f32_e32 v56, v56, v170
	v_add_f32_e32 v57, v57, v171
	v_add_f32_e32 v50, v50, v172
	v_add_f32_e32 v51, v51, v173
	v_add_f32_e32 v52, v52, v174
	v_add_f32_e32 v53, v53, v175
	s_mov_b32 s2, 0x22000
	v_lshl_add_u64 v[186:187], v[182:183], 0, s[2:3]
	global_store_dwordx4 v[186:187], v[54:57], off
	global_store_dwordx4 v[186:187], v[50:53], off offset:16
	s_add_u32 s2, s15, 0x140000
	v_lshl_add_u64 v[184:185], v[176:177], 0, s[2:3]
	global_load_dwordx4 v[168:171], v[184:185], off
	global_load_dwordx4 v[172:175], v[184:185], off offset:16
	s_waitcnt vmcnt(16)
	v_add_f32_e32 v46, v46, v130
	v_add_f32_e32 v47, v47, v131
	v_add_f32_e32 v48, v48, v132
	v_add_f32_e32 v49, v49, v133
	v_add_f32_e32 v42, v42, v134
	v_add_f32_e32 v43, v43, v135
	v_add_f32_e32 v44, v44, v136
	v_add_f32_e32 v45, v45, v137
	s_mov_b32 s2, 0x42000
	v_lshl_add_u64 v[186:187], v[182:183], 0, s[2:3]
	global_store_dwordx4 v[186:187], v[46:49], off
	global_store_dwordx4 v[186:187], v[42:45], off offset:16
	s_add_u32 s2, s15, 0x160000
	v_lshl_add_u64 v[184:185], v[176:177], 0, s[2:3]
	global_load_dwordx4 v[130:133], v[184:185], off
	global_load_dwordx4 v[134:137], v[184:185], off offset:16
	s_waitcnt vmcnt(16)
	v_add_f32_e32 v38, v38, v138
	v_add_f32_e32 v39, v39, v139
	v_add_f32_e32 v40, v40, v140
	v_add_f32_e32 v41, v41, v141
	v_add_f32_e32 v34, v34, v142
	v_add_f32_e32 v35, v35, v143
	v_add_f32_e32 v36, v36, v144
	v_add_f32_e32 v37, v37, v145
	s_mov_b32 s2, 0x62000
	v_lshl_add_u64 v[186:187], v[182:183], 0, s[2:3]
	global_store_dwordx4 v[186:187], v[38:41], off
	global_store_dwordx4 v[186:187], v[34:37], off offset:16
	s_waitcnt vmcnt(14)
	v_add_f32_e32 v30, v30, v146
	v_add_f32_e32 v31, v31, v147
	v_add_f32_e32 v32, v32, v148
	v_add_f32_e32 v33, v33, v149
	v_add_f32_e32 v26, v26, v150
	v_add_f32_e32 v27, v27, v151
	v_add_f32_e32 v28, v28, v152
	v_add_f32_e32 v29, v29, v153
	s_mov_b32 s2, 0x102000
	v_lshl_add_u64 v[186:187], v[182:183], 0, s[2:3]
	global_store_dwordx4 v[186:187], v[30:33], off
	global_store_dwordx4 v[186:187], v[26:29], off offset:16
	s_waitcnt vmcnt(12)
	v_add_f32_e32 v22, v22, v154
	v_add_f32_e32 v23, v23, v155
	v_add_f32_e32 v24, v24, v156
	v_add_f32_e32 v25, v25, v157
	v_add_f32_e32 v18, v18, v158
	v_add_f32_e32 v19, v19, v159
	v_add_f32_e32 v20, v20, v160
	v_add_f32_e32 v21, v21, v161
	s_mov_b32 s2, 0x122000
	v_lshl_add_u64 v[186:187], v[182:183], 0, s[2:3]
	global_store_dwordx4 v[186:187], v[22:25], off
	global_store_dwordx4 v[186:187], v[18:21], off offset:16
	s_waitcnt vmcnt(10)
	v_add_f32_e32 v14, v14, v168
	v_add_f32_e32 v15, v15, v169
	v_add_f32_e32 v16, v16, v170
	v_add_f32_e32 v17, v17, v171
	v_add_f32_e32 v10, v10, v172
	v_add_f32_e32 v11, v11, v173
	v_add_f32_e32 v12, v12, v174
	v_add_f32_e32 v13, v13, v175
	s_mov_b32 s2, 0x142000
	v_lshl_add_u64 v[186:187], v[182:183], 0, s[2:3]
	global_store_dwordx4 v[186:187], v[14:17], off
	global_store_dwordx4 v[186:187], v[10:13], off offset:16
	s_waitcnt vmcnt(8)
	v_add_f32_e32 v6, v6, v130
	v_add_f32_e32 v7, v7, v131
	v_add_f32_e32 v8, v8, v132
	v_add_f32_e32 v9, v9, v133
	v_add_f32_e32 v2, v2, v134
	v_add_f32_e32 v3, v3, v135
	v_add_f32_e32 v4, v4, v136
	v_add_f32_e32 v5, v5, v137
	s_mov_b32 s2, 0x162000
	v_lshl_add_u64 v[186:187], v[182:183], 0, s[2:3]
	global_store_dwordx4 v[186:187], v[6:9], off
	global_store_dwordx4 v[186:187], v[2:5], off offset:16
	s_andn2_b64 vcc, exec, s[18:19]
	s_mov_b64 s[0:1], -1
	s_cbranch_vccnz .LBB0_928
	s_andn2_b64 vcc, exec, s[4:5]
	s_cbranch_vccnz .LBB0_927
	s_barrier
	s_branch .LBB0_927

.LBB0_1057:
	s_cmp_le_i32 s76, s16
	s_cselect_b64 s[0:1], -1, 0
	s_cmp_lt_i32 s16, s77
	s_cselect_b64 s[2:3], -1, 0
	s_and_b64 s[0:1], s[0:1], s[2:3]
	s_andn2_b64 vcc, exec, s[0:1]
	s_cbranch_vccnz .LBB0_55
	v_readlane_b32 s0, v236, 2
	v_readlane_b32 s1, v236, 3
	s_andn2_b64 vcc, exec, s[0:1]
	s_mov_b64 s[0:1], -1
	s_cbranch_vccnz .LBB0_1063
	v_mov_b32_e32 v0, v212
	s_waitcnt vmcnt(1)
	v_mov_b32_e32 v2, v212
	v_readlane_b32 s0, v239, 5
	s_waitcnt vmcnt(0)
	v_ashrrev_i32_e32 v6, 6, v2
	v_add_u32_e32 v70, s0, v6
	s_movk_i32 s0, 0x4000
	v_cmp_gt_i32_e32 vcc, s0, v70
	s_and_saveexec_b64 s[0:1], vcc
	v_readlane_b32 s8, v238, 31
	v_readlane_b32 s9, v238, 32
	v_readlane_b32 s10, v239, 6
	v_readlane_b32 s12, v237, 21
	v_readlane_b32 s11, v239, 7
	v_readlane_b32 s13, v237, 22
	s_cbranch_execz .LBB0_1062
	v_readlane_b32 s2, v236, 1
	s_lshl_b32 s72, s2, 11
	v_readlane_b32 s4, v239, 8
	s_lshl_b64 s[2:3], s[72:73], 2
	v_readlane_b32 s6, v239, 10
	v_readlane_b32 s7, v239, 11
	s_add_u32 s2, s6, s2
	s_addc_u32 s3, s7, s3
	v_lshlrev_b32_e32 v2, 2, v0
	s_add_u32 s2, s2, 0x2000
	v_and_b32_e32 v7, 0xfc, v2
	s_addc_u32 s3, s3, 0
	v_and_b32_e32 v71, 28, v2
	v_and_b32_e32 v3, 64, v218
	v_bfe_u32 v73, v2, 5, 3
	v_lshlrev_b32_e32 v2, 2, v7
	v_add_u32_e32 v8, 64, v3
	global_load_dwordx4 v[2:5], v2, s[2:3]
	v_xor_b32_e32 v10, 32, v218
	v_cmp_lt_i32_e32 vcc, v10, v8
	v_bfe_u32 v72, v0, 3, 1
	v_or_b32_e32 v9, 0x100, v7
	v_cndmask_b32_e32 v10, v218, v10, vcc
	v_lshlrev_b32_e32 v81, 2, v10
	v_xor_b32_e32 v10, 16, v218
	v_cmp_lt_i32_e32 vcc, v10, v8
	v_lshlrev_b32_e32 v0, 10, v0
	v_or_b32_e32 v11, 0x200, v7
	v_cndmask_b32_e32 v10, v218, v10, vcc
	v_lshlrev_b32_e32 v82, 2, v10
	v_xor_b32_e32 v10, 8, v218
	v_cmp_lt_i32_e32 vcc, v10, v8
	v_or_b32_e32 v13, 0x300, v7
	v_or_b32_e32 v15, 0x400, v7
	v_cndmask_b32_e32 v10, v218, v10, vcc
	v_lshlrev_b32_e32 v83, 2, v10
	v_xor_b32_e32 v10, 4, v218
	v_cmp_lt_i32_e32 vcc, v10, v8
	v_or_b32_e32 v17, 0x500, v7
	v_or_b32_e32 v19, 0x600, v7
	v_cndmask_b32_e32 v10, v218, v10, vcc
	v_lshlrev_b32_e32 v84, 2, v10
	v_xor_b32_e32 v10, 2, v218
	v_cmp_lt_i32_e32 vcc, v10, v8
	v_or_b32_e32 v7, 0x700, v7
	v_readlane_b32 s5, v239, 9
	v_cndmask_b32_e32 v10, v218, v10, vcc
	v_lshlrev_b32_e32 v85, 2, v10
	v_xor_b32_e32 v10, 1, v218
	v_cmp_lt_i32_e32 vcc, v10, v8
	v_lshrrev_b32_e32 v74, 5, v9
	v_lshrrev_b32_e32 v75, 5, v11
	v_cndmask_b32_e32 v8, v218, v10, vcc
	v_lshlrev_b32_e32 v86, 2, v8
	v_and_b32_e32 v8, 0xc000, v0
	v_lshlrev_b32_e32 v0, 2, v9
	v_lshl_add_u64 v[38:39], s[2:3], 0, v[0:1]
	v_lshlrev_b32_e32 v0, 8, v9
	v_and_b32_e32 v10, 0x1c000, v0
	v_lshlrev_b32_e32 v0, 2, v11
	v_lshl_add_u64 v[40:41], s[2:3], 0, v[0:1]
	v_lshlrev_b32_e32 v0, 8, v11
	v_and_b32_e32 v12, 0x2c000, v0
	v_lshlrev_b32_e32 v0, 2, v13
	v_lshl_add_u64 v[42:43], s[2:3], 0, v[0:1]
	v_lshlrev_b32_e32 v0, 8, v13
	v_and_b32_e32 v14, 0x3c000, v0
	v_lshlrev_b32_e32 v0, 2, v15
	v_lshl_add_u64 v[44:45], s[2:3], 0, v[0:1]
	v_lshlrev_b32_e32 v0, 8, v15
	v_and_b32_e32 v16, 0x4c000, v0
	v_lshlrev_b32_e32 v0, 2, v17
	v_lshl_add_u64 v[46:47], s[2:3], 0, v[0:1]
	v_lshlrev_b32_e32 v0, 8, v17
	v_and_b32_e32 v18, 0x5c000, v0
	v_lshlrev_b32_e32 v0, 2, v19
	v_lshl_add_u64 v[48:49], s[2:3], 0, v[0:1]
	v_lshlrev_b32_e32 v0, 8, v19
	v_and_b32_e32 v20, 0x6c000, v0
	v_lshlrev_b32_e32 v0, 2, v7
	v_lshl_add_u64 v[50:51], s[2:3], 0, v[0:1]
	v_readlane_b32 s2, v239, 4
	v_lshlrev_b32_e32 v0, 8, v7
	v_and_b32_e32 v0, 0x7c000, v0
	v_lshl_add_u32 v87, v6, 6, s2
	v_readlane_b32 s2, v237, 7
	v_lshrrev_b32_e32 v76, 5, v13
	v_lshrrev_b32_e32 v77, 5, v15
	v_lshl_add_u32 v88, v6, 5, s2
	v_readlane_b32 s2, v237, 8
	v_lshrrev_b32_e32 v78, 5, v17
	v_lshrrev_b32_e32 v79, 5, v19
	v_lshrrev_b32_e32 v80, 5, v7
	v_lshl_add_u32 v89, v6, 2, s2
	s_mov_b64 s[4:5], 0
	v_lshlrev_b32_e32 v52, 1, v8
	v_lshlrev_b32_e32 v54, 1, v10
	v_lshlrev_b32_e32 v56, 1, v12
	v_lshlrev_b32_e32 v58, 1, v14
	v_lshlrev_b32_e32 v60, 1, v16
	v_lshlrev_b32_e32 v62, 1, v18
	v_lshlrev_b32_e32 v64, 1, v20
	v_lshlrev_b32_e32 v66, 1, v0
	global_load_dwordx4 v[100:103], v[38:39], off
	global_load_dwordx4 v[104:107], v[40:41], off
	global_load_dwordx4 v[108:111], v[42:43], off
	global_load_dwordx4 v[112:115], v[44:45], off
	global_load_dwordx4 v[116:119], v[46:47], off
	global_load_dwordx4 v[120:123], v[48:49], off
	global_load_dwordx4 v[124:127], v[50:51], off
.LBB0_1061:
	v_and_b32_e32 v53, 0xffffffc0, v89
	v_and_or_b32 v0, v88, s39, v71
	v_lshlrev_b32_e32 v0, 2, v0
	v_or_b32_e32 v6, v53, v73
	v_ashrrev_i32_e32 v7, 31, v6
	v_lshlrev_b64 v[6:7], 11, v[6:7]
	v_lshl_add_u64 v[6:7], s[8:9], 0, v[6:7]
	v_lshl_add_u64 v[6:7], v[6:7], 0, v[0:1]
	global_load_dwordx4 v[34:37], v[6:7], off
	v_or_b32_e32 v6, v53, v74
	v_ashrrev_i32_e32 v7, 31, v6
	v_lshlrev_b64 v[6:7], 11, v[6:7]
	v_lshl_add_u64 v[6:7], s[8:9], 0, v[6:7]
	v_lshl_add_u64 v[6:7], v[6:7], 0, v[0:1]
	global_load_dwordx4 v[30:33], v[6:7], off
	v_or_b32_e32 v6, v53, v75
	v_ashrrev_i32_e32 v7, 31, v6
	v_lshlrev_b64 v[6:7], 11, v[6:7]
	v_lshl_add_u64 v[6:7], s[8:9], 0, v[6:7]
	v_lshl_add_u64 v[6:7], v[6:7], 0, v[0:1]
	global_load_dwordx4 v[26:29], v[6:7], off
	v_or_b32_e32 v6, v53, v76
	v_ashrrev_i32_e32 v7, 31, v6
	v_lshlrev_b64 v[6:7], 11, v[6:7]
	v_lshl_add_u64 v[6:7], s[8:9], 0, v[6:7]
	v_lshl_add_u64 v[6:7], v[6:7], 0, v[0:1]
	global_load_dwordx4 v[22:25], v[6:7], off
	v_or_b32_e32 v6, v53, v77
	v_ashrrev_i32_e32 v7, 31, v6
	v_lshlrev_b64 v[6:7], 11, v[6:7]
	v_lshl_add_u64 v[6:7], s[8:9], 0, v[6:7]
	v_lshl_add_u64 v[6:7], v[6:7], 0, v[0:1]
	global_load_dwordx4 v[18:21], v[6:7], off
	v_or_b32_e32 v6, v53, v78
	v_ashrrev_i32_e32 v7, 31, v6
	v_lshlrev_b64 v[6:7], 11, v[6:7]
	v_lshl_add_u64 v[6:7], s[8:9], 0, v[6:7]
	v_lshl_add_u64 v[6:7], v[6:7], 0, v[0:1]
	global_load_dwordx4 v[14:17], v[6:7], off
	v_or_b32_e32 v6, v53, v79
	v_ashrrev_i32_e32 v7, 31, v6
	v_lshlrev_b64 v[6:7], 11, v[6:7]
	v_lshl_add_u64 v[6:7], s[8:9], 0, v[6:7]
	v_lshl_add_u64 v[6:7], v[6:7], 0, v[0:1]
	global_load_dwordx4 v[96:99], v[6:7], off
	v_or_b32_e32 v6, v53, v80
	v_ashrrev_i32_e32 v7, 31, v6
	v_lshlrev_b64 v[6:7], 11, v[6:7]
	v_lshl_add_u64 v[6:7], s[8:9], 0, v[6:7]
	v_lshl_add_u64 v[6:7], v[6:7], 0, v[0:1]
	global_load_dwordx4 v[92:95], v[6:7], off
	v_lshlrev_b32_e32 v57, 1, v70
	v_and_b32_e32 v57, 16, v57
	v_mov_b32_e32 v59, v1
	v_mov_b32_e32 v61, v1
	v_mov_b32_e32 v63, v1
	v_mov_b32_e32 v65, v1
	v_add_u32_e32 v88, s18, v88
	v_add_u32_e32 v89, s38, v89
	s_waitcnt vmcnt(7)
	v_mul_f32_e32 v8, v35, v35
	v_fmac_f32_e32 v8, v34, v34
	v_fmac_f32_e32 v8, v36, v36
	v_fmac_f32_e32 v8, v37, v37
	s_waitcnt vmcnt(6)
	v_mul_f32_e32 v6, v31, v31
	v_fmac_f32_e32 v6, v30, v30
	v_fmac_f32_e32 v6, v32, v32
	v_fmac_f32_e32 v6, v33, v33
	v_add_f32_e32 v8, v8, v6
	s_waitcnt vmcnt(5)
	v_mul_f32_e32 v6, v27, v27
	v_fmac_f32_e32 v6, v26, v26
	v_fmac_f32_e32 v6, v28, v28
	v_fmac_f32_e32 v6, v29, v29
	v_add_f32_e32 v8, v8, v6
	s_waitcnt vmcnt(4)
	v_mul_f32_e32 v6, v23, v23
	v_fmac_f32_e32 v6, v22, v22
	v_fmac_f32_e32 v6, v24, v24
	v_fmac_f32_e32 v6, v25, v25
	v_add_f32_e32 v10, v8, v6
	s_waitcnt vmcnt(3)
	v_mov_b32_e32 v8, v19
	v_mov_b32_e32 v6, v18
	s_waitcnt vmcnt(2)
	v_mov_b32_e32 v9, v15
	v_mov_b32_e32 v7, v14
	v_pk_mul_f32 v[8:9], v[8:9], v[8:9]
	s_nop 0
	v_pk_fma_f32 v[6:7], v[6:7], v[6:7], v[8:9]
	v_mov_b32_e32 v8, v20
	v_mov_b32_e32 v9, v16
	v_pk_fma_f32 v[6:7], v[8:9], v[8:9], v[6:7]
	v_mov_b32_e32 v8, v21
	v_mov_b32_e32 v9, v17
	v_pk_fma_f32 v[6:7], v[8:9], v[8:9], v[6:7]
	s_nop 0
	v_add_f32_e32 v6, v10, v6
	v_add_f32_e32 v55, v6, v7
	s_waitcnt vmcnt(1)
	v_mov_b32_e32 v10, v96
	v_mov_b32_e32 v11, v97
	v_mov_b32_e32 v12, v98
	v_mov_b32_e32 v13, v99
	v_mov_b32_e32 v90, v11
	v_mov_b32_e32 v68, v10
	s_waitcnt vmcnt(0)
	v_mov_b32_e32 v6, v92
	v_mov_b32_e32 v7, v93
	v_mov_b32_e32 v8, v94
	v_mov_b32_e32 v9, v95
	v_mov_b32_e32 v91, v7
	v_mov_b32_e32 v69, v6
	v_pk_mul_f32 v[90:91], v[90:91], v[90:91]
	s_nop 0
	v_pk_fma_f32 v[68:69], v[68:69], v[68:69], v[90:91]
	v_mov_b32_e32 v90, v12
	v_mov_b32_e32 v91, v8
	v_pk_fma_f32 v[68:69], v[90:91], v[90:91], v[68:69]
	v_mov_b32_e32 v90, v13
	v_mov_b32_e32 v91, v9
	v_pk_fma_f32 v[68:69], v[90:91], v[90:91], v[68:69]
	s_nop 0
	v_add_f32_e32 v0, v55, v68
	v_add_f32_e32 v0, v0, v69
	ds_bpermute_b32 v53, v81, v0
	v_ashrrev_i32_e32 v68, 8, v70
	v_ashrrev_i32_e32 v69, 31, v68
	v_lshlrev_b32_e32 v55, 5, v70
	v_and_b32_e32 v55, 0x1e0, v55
	s_waitcnt lgkmcnt(0)
	v_add_f32_e32 v0, v0, v53
	ds_bpermute_b32 v53, v82, v0
	v_lshlrev_b64 v[68:69], 20, v[68:69]
	v_bitop3_b32 v55, v55, v57, v71 bitop3:0x36
	v_lshl_add_u64 v[68:69], s[84:85], 0, v[68:69]
	v_mov_b32_e32 v57, v1
	s_waitcnt lgkmcnt(0)
	v_add_f32_e32 v0, v0, v53
	ds_bpermute_b32 v53, v83, v0
	s_waitcnt lgkmcnt(0)
	v_add_f32_e32 v0, v0, v53
	ds_bpermute_b32 v53, v84, v0
	s_waitcnt lgkmcnt(0)
	v_add_f32_e32 v0, v0, v53
	ds_bpermute_b32 v53, v85, v0
	s_waitcnt lgkmcnt(0)
	v_add_f32_e32 v0, v0, v53
	ds_bpermute_b32 v53, v86, v0
	s_waitcnt lgkmcnt(0)
	v_add_f32_e32 v0, v0, v53
	v_fmamk_f32 v0, v0, 0x3a000000, v215
	v_cmp_gt_f32_e32 vcc, s40, v0
	v_mul_f32_e32 v53, 0x4b800000, v0
	s_nop 0
	v_cndmask_b32_e32 v0, v0, v53, vcc
	v_rsq_f32_e32 v0, v0
	s_nop 0
	v_mul_f32_e32 v53, 0x45800000, v0
	v_cndmask_b32_e32 v67, v0, v53, vcc
	v_and_b32_e32 v0, 0x2000, v87
	v_lshrrev_b32_e32 v53, 3, v70
	v_lshlrev_b32_e32 v0, 1, v0
	v_and_or_b32 v53, v53, 14, v72
	v_lshl_add_u64 v[68:69], v[68:69], 0, v[0:1]
	v_lshlrev_b32_e32 v0, 1, v55
	v_lshl_or_b32 v0, v53, 10, v0
	v_lshl_add_u64 v[68:69], v[68:69], 0, v[0:1]
	v_mul_f32_e32 v0, v34, v67
	v_mul_f32_e32 v34, v35, v67
	v_mul_f32_e32 v35, v36, v67
	v_mul_f32_e32 v36, v37, v67
	v_mul_f32_e32 v34, v3, v34
	v_mul_f32_e32 v35, v4, v35
	v_mul_f32_e32 v36, v5, v36
	v_mov_b32_e32 v53, v1
	v_mul_f32_e32 v0, v2, v0
	v_cvt_pk_bf16_f32 v34, v0, v34
	v_cvt_pk_bf16_f32 v35, v35, v36
	v_lshl_add_u64 v[36:37], v[68:69], 0, v[52:53]
	global_store_dwordx2 v[36:37], v[34:35], off
	v_mul_f32_e32 v0, v30, v67
	v_mul_f32_e32 v30, v31, v67
	v_mul_f32_e32 v31, v32, v67
	v_mul_f32_e32 v32, v33, v67
	v_mov_b32_e32 v55, v1
	v_add_u32_e32 v70, s12, v70
	v_cmp_lt_i32_e32 vcc, s41, v70
	v_add_u32_e32 v87, s10, v87
	s_or_b64 s[4:5], vcc, s[4:5]
	v_mov_b32_e32 v34, v100
	v_mov_b32_e32 v35, v101
	v_mov_b32_e32 v36, v102
	v_mov_b32_e32 v37, v103
	v_mul_f32_e32 v30, v35, v30
	v_mul_f32_e32 v31, v36, v31
	v_mul_f32_e32 v32, v37, v32
	v_mul_f32_e32 v0, v34, v0
	v_cvt_pk_bf16_f32 v30, v0, v30
	v_cvt_pk_bf16_f32 v31, v31, v32
	v_lshl_add_u64 v[32:33], v[68:69], 0, v[54:55]
	global_store_dwordx2 v[32:33], v[30:31], off
	v_mul_f32_e32 v0, v26, v67
	v_mul_f32_e32 v26, v27, v67
	v_mul_f32_e32 v27, v28, v67
	v_mul_f32_e32 v28, v29, v67
	v_mov_b32_e32 v30, v104
	v_mov_b32_e32 v31, v105
	v_mov_b32_e32 v32, v106
	v_mov_b32_e32 v33, v107
	v_mul_f32_e32 v26, v31, v26
	v_mul_f32_e32 v27, v32, v27
	v_mul_f32_e32 v28, v33, v28
	v_mul_f32_e32 v0, v30, v0
	v_cvt_pk_bf16_f32 v26, v0, v26
	v_cvt_pk_bf16_f32 v27, v27, v28
	v_lshl_add_u64 v[28:29], v[68:69], 0, v[56:57]
	global_store_dwordx2 v[28:29], v[26:27], off
	v_mul_f32_e32 v0, v22, v67
	v_mul_f32_e32 v22, v23, v67
	v_mul_f32_e32 v23, v24, v67
	v_mul_f32_e32 v24, v25, v67
	v_mov_b32_e32 v26, v108
	v_mov_b32_e32 v27, v109
	v_mov_b32_e32 v28, v110
	v_mov_b32_e32 v29, v111
	v_mul_f32_e32 v22, v27, v22
	v_mul_f32_e32 v23, v28, v23
	v_mul_f32_e32 v24, v29, v24
	v_mul_f32_e32 v0, v26, v0
	v_cvt_pk_bf16_f32 v22, v0, v22
	v_cvt_pk_bf16_f32 v23, v23, v24
	v_lshl_add_u64 v[24:25], v[68:69], 0, v[58:59]
	global_store_dwordx2 v[24:25], v[22:23], off
	v_mul_f32_e32 v0, v18, v67
	v_mul_f32_e32 v18, v19, v67
	v_mul_f32_e32 v19, v20, v67
	v_mul_f32_e32 v20, v21, v67
	v_mov_b32_e32 v22, v112
	v_mov_b32_e32 v23, v113
	v_mov_b32_e32 v24, v114
	v_mov_b32_e32 v25, v115
	v_mul_f32_e32 v18, v18, v23
	v_mul_f32_e32 v19, v19, v24
	v_mul_f32_e32 v20, v20, v25
	v_mul_f32_e32 v0, v0, v22
	v_cvt_pk_bf16_f32 v18, v0, v18
	v_cvt_pk_bf16_f32 v19, v19, v20
	v_lshl_add_u64 v[20:21], v[68:69], 0, v[60:61]
	global_store_dwordx2 v[20:21], v[18:19], off
	v_mul_f32_e32 v0, v14, v67
	v_mul_f32_e32 v14, v15, v67
	v_mul_f32_e32 v15, v16, v67
	v_mul_f32_e32 v16, v17, v67
	v_mov_b32_e32 v18, v116
	v_mov_b32_e32 v19, v117
	v_mov_b32_e32 v20, v118
	v_mov_b32_e32 v21, v119
	v_mul_f32_e32 v14, v14, v19
	v_mul_f32_e32 v15, v15, v20
	v_mul_f32_e32 v16, v16, v21
	v_mul_f32_e32 v0, v0, v18
	v_cvt_pk_bf16_f32 v14, v0, v14
	v_cvt_pk_bf16_f32 v15, v15, v16
	v_lshl_add_u64 v[16:17], v[68:69], 0, v[62:63]
	global_store_dwordx2 v[16:17], v[14:15], off
	v_mul_f32_e32 v0, v10, v67
	v_mul_f32_e32 v10, v11, v67
	v_mul_f32_e32 v11, v12, v67
	v_mul_f32_e32 v12, v13, v67
	v_mov_b32_e32 v14, v120
	v_mov_b32_e32 v15, v121
	v_mov_b32_e32 v16, v122
	v_mov_b32_e32 v17, v123
	v_mul_f32_e32 v10, v10, v15
	v_mul_f32_e32 v11, v11, v16
	v_mul_f32_e32 v12, v12, v17
	v_mul_f32_e32 v0, v0, v14
	v_cvt_pk_bf16_f32 v10, v0, v10
	v_cvt_pk_bf16_f32 v11, v11, v12
	v_lshl_add_u64 v[12:13], v[68:69], 0, v[64:65]
	global_store_dwordx2 v[12:13], v[10:11], off
	v_mul_f32_e32 v0, v6, v67
	v_mul_f32_e32 v6, v7, v67
	v_mul_f32_e32 v7, v8, v67
	v_mul_f32_e32 v8, v9, v67
	v_mov_b32_e32 v67, v1
	v_mov_b32_e32 v10, v124
	v_mov_b32_e32 v11, v125
	v_mov_b32_e32 v12, v126
	v_mov_b32_e32 v13, v127
	v_mul_f32_e32 v7, v7, v12
	v_mul_f32_e32 v8, v8, v13
	v_mul_f32_e32 v6, v6, v11
	v_cvt_pk_bf16_f32 v7, v7, v8
	v_lshl_add_u64 v[8:9], v[68:69], 0, v[66:67]
	v_mul_f32_e32 v0, v0, v10
	v_cvt_pk_bf16_f32 v6, v0, v6
	global_store_dwordx2 v[8:9], v[6:7], off
	s_andn2_b64 exec, exec, s[4:5]
	s_cbranch_execnz .LBB0_1061
